# MFMA-shadow fill: DIFF loop's 16 p0 v_exp issued one per P.V MFMA gap into free v236-251 (speculating no rescale; rare path recomputes)
# speedup vs baseline: 1.0026x; 1.0026x over previous
; __device__ __forceinline__ int v_st(int k, int c) { const int kk = (k & ~0xC) | ((k & 4) << 1) | ((k & 8) >> 1); return ((kk >> 3) * 4 + (c >> 5)) * 512 + ((kk & 7) * 32 + (c & 31)) * 2; }
; __device__ __forceinline__ int v_rd_base(int lane) { return ((lane & 3) << 3) | (((lane >> 2) & 3) << 6) | (((lane >> 4) & 1) << 5) | (((lane >> 5) & 1) << 8); }
; #define SWRITE(b, i) do { *(bf16x8*)(V_lds + (b) * SHM_V + vst0) = sr_[i].vs0; *(bf16x8*)(V_lds + (b) * SHM_V + vst1) = sr_[i].vs1; \
;     *(bf16x8*)(K_lds + (b) * SHM_K + kdst0) = sr_[i].ks0; *(bf16x8*)(K_lds + (b) * SHM_K + kdst0 + 32 * KW * 2) = sr_[i].ks1; \
;     if constexpr (KW == 192) *(bf16x8*)(K_lds + (b) * SHM_K + kdst2) = sr_[i].ks2; } while (0)
; #define VM0() asm volatile("s_waitcnt vmcnt(0)" ::: "memory")
; #define WGBAR() asm volatile("s_waitcnt lgkmcnt(0)\n\ts_barrier" ::: "memory")
; template <int DQK, int KW, bool DIFF, int SDEPTH, int QSP, int NBUF>
; __device__ __forceinline__ void attn_unit(const UnitP& P, char* lds) {
;     ...
;   { const bf16_t* Qp = P.Qw + (long)r32 * P.ldq + hi * 8;
; #pragma unroll
;     for (int d0 = 0; d0 < NQR; ++d0) qr[d0] = *reinterpret_cast<const bf16x8*>(Qp + d0 * 16);
; #pragma unroll
;     for (int d0 = NQR; d0 < DQK / 16; ++d0) *reinterpret_cast<bf16x8*>(qsp + (d0 - NQR) * 1024) = *reinterpret_cast<const bf16x8*>(Qp + d0 * 16); }
;   const int sr = tid >> 4, sc = (tid & 15) * 8, vst0 = v_st(sr, sc), vst1 = v_st(32 + sr, sc);
;   const int vb0 = (int)(uintptr_t)V_lds + v_rd_base(lane);
;   int kb[4];
; #pragma unroll
;   for (int q = 0; q < 4; ++q) kb[q] = coffB + kswz<KW>(r32, q * 32 + hi * 16);
;   const unsigned voff = (unsigned)(sr * P.ldv + sc) * 2u, koff = (unsigned)(sr * P.ldk0 + sc) * 2u, koff2 = (unsigned)((tid >> 3) * P.ldk1 + (tid & 7) * 8) * 2u;
;   const int kdst0 = kswz<KW>(sr, sc * 2), kdst2 = kswz<KW>(tid >> 3, 256 + (tid & 7) * 16);
;   struct { bf16x8 vs0, vs1, ks0, ks1, ks2; } sr_[SDEPTH];
;     ...
;   f32x16 pA0, pA1, pB0, pB1; float mnA, mnB, alA, alB; bf16x8 pa0, pa1, pa2, pa3; const int NT = P.nt;
;   if constexpr (NBUF == 3) {
;     ...
;     int rprev = 0, rcur = 1, rnext = 2;
;     SLOAD(0, 0); VM0(); SWRITE(0, 0); SLOAD(0, 1); WGBAR();
.LBB0_315:
	s_ashr_i32 s36, s33, 4
	s_ashr_i32 s10, s2, 31
	s_add_u32 s2, s2, s26
	s_mul_i32 s7, s36, 0x900
	s_addc_u32 s11, s10, 0
	s_mul_hi_i32 s6, s36, 0x900
	s_add_u32 s10, s2, s7
	s_addc_u32 s11, s11, s6
	s_add_u32 s12, s7, s8
	s_addc_u32 s13, s6, s9
	s_lshl_b64 s[6:7], s[10:11], 11
	s_lshl_b64 s[10:11], s[10:11], 12
	s_add_u32 s9, s15, s10
	s_addc_u32 s10, s16, s11
	s_lshl_b32 s2, s33, 7
	s_and_b32 s2, s2, 0x780
	s_lshl_b32 s35, s2, 1
	s_add_u32 s9, s9, s35
	s_addc_u32 s10, s10, 0
	s_add_u32 s38, s9, s40
	s_addc_u32 s39, s10, s41
	s_lshl_b64 s[12:13], s[12:13], 12
	s_add_u32 s9, s17, s12
	s_addc_u32 s11, s19, s13
	s_add_u32 s10, s9, s35
	s_addc_u32 s11, s11, 0
	v_mov_b32_e32 v176, v184
	v_mov_b32_e32 v2, v1
	v_mov_b32_e32 v3, v1
	v_mov_b32_e32 v4, v1
	v_mov_b32_e32 v5, v1
	v_mov_b32_e32 v6, v1
	v_mov_b32_e32 v7, v1
	v_mov_b32_e32 v8, v1
	v_mov_b32_e32 v9, v1
	v_mov_b32_e32 v10, v1
	v_mov_b32_e32 v11, v1
	v_mov_b32_e32 v12, v1
	v_mov_b32_e32 v13, v1
	v_mov_b32_e32 v14, v1
	v_mov_b32_e32 v15, v1
	s_add_u32 s9, s20, s12
	v_mov_b32_e32 v0, v1
	v_and_b32_e32 v162, 31, v176
	v_mov_b64_e32 v[16:17], v[14:15]
	v_lshlrev_b32_e32 v37, 3, v176
	s_addc_u32 s13, s21, s13
	v_mov_b64_e32 v[14:15], v[12:13]
	v_mov_b64_e32 v[12:13], v[10:11]
	v_mov_b64_e32 v[10:11], v[8:9]
	v_mov_b64_e32 v[8:9], v[6:7]
	v_mov_b64_e32 v[6:7], v[4:5]
	v_mov_b64_e32 v[4:5], v[2:3]
	v_mov_b64_e32 v[2:3], v[0:1]
	v_lshlrev_b32_e32 v0, 12, v162
	v_and_b32_e32 v174, 0x78, v37
	s_add_u32 s12, s9, s35
	v_lshl_add_u64 v[34:35], s[38:39], 0, v[0:1]
	v_ashrrev_i32_e32 v36, 4, v176
	v_lshlrev_b32_e32 v0, 1, v174
	s_addc_u32 s13, s13, 0
	v_lshl_or_b32 v46, v36, 12, v0
	v_mov_b32_e32 v47, v1
	v_lshl_add_u64 v[50:51], s[12:13], 0, v[46:47]
	v_add_co_u32_e32 v18, vcc, s87, v50
	v_lshl_add_u64 v[48:49], s[10:11], 0, v[46:47]
	s_nop 0
	v_addc_co_u32_e32 v19, vcc, 0, v51, vcc
	global_load_dwordx4 v[18:21], v[18:19], off
	s_nop 0
	global_load_dwordx4 v[22:25], v46, s[12:13]
	global_load_dwordx4 v[26:29], v46, s[10:11]
	v_add_co_u32_e32 v30, vcc, s87, v48
	v_bfe_u32 v175, v176, 5, 1
	s_nop 0
	v_addc_co_u32_e32 v31, vcc, 0, v49, vcc
	global_load_dwordx4 v[30:33], v[30:31], off
	v_lshlrev_b32_e32 v164, 4, v175
	v_mov_b32_e32 v165, v1
	v_lshl_add_u64 v[34:35], v[34:35], 0, v[164:165]
	global_load_dwordx4 v[142:145], v[34:35], off
	global_load_dwordx4 v[138:141], v[34:35], off offset:32
	global_load_dwordx4 v[134:137], v[34:35], off offset:64
	global_load_dwordx4 v[130:133], v[34:35], off offset:96
	v_and_b32_e32 v34, 0xfffff0, v36
	v_lshlrev_b32_e32 v35, 1, v36
	v_and_or_b32 v34, v35, 8, v34
	v_lshrrev_b32_e32 v35, 1, v36
	v_and_b32_e32 v38, 3, v36
	v_and_or_b32 v35, v35, 4, v38
	v_add_u32_e32 v38, 32, v36
	v_and_b32_e32 v39, 0xfffff0, v38
	v_lshlrev_b32_e32 v38, 1, v38
	v_and_or_b32 v38, v38, 8, v39
	v_lshrrev_b32_e32 v34, 1, v34
	v_bfe_u32 v37, v37, 5, 2
	v_lshrrev_b32_e32 v38, 1, v38
	v_ashrrev_i32_e32 v165, 8, v176
	v_or_b32_e32 v34, v34, v37
	v_or_b32_e32 v37, v38, v37
	v_lshlrev_b32_e32 v38, 8, v162
	v_lshlrev_b32_e32 v34, 9, v34
	v_lshlrev_b32_e32 v35, 6, v35
	v_lshlrev_b32_e32 v37, 9, v37
	v_lshl_add_u32 v73, v165, 7, v38
	v_and_b32_e32 v38, 48, v0
	v_or3_b32 v192, v34, v35, v38
	v_or3_b32 v193, v37, v35, v38
	v_add_u32_e32 v99, 0, v192
	v_add_u32_e32 v100, 0, v193
	v_lshlrev_b32_e32 v34, 8, v36
	v_and_b32_e32 v35, 0x70, v176
	s_waitcnt vmcnt(0)
	v_bitop3_b32 v194, v0, v34, v35 bitop3:0xde
	v_add_u32_e32 v195, 0, v194
	v_lshlrev_b32_e32 v98, 4, v176
	v_and_b32_e32 v72, 0x70, v98
	v_bitop3_b32 v183, v164, v73, v72 bitop3:0xde
	s_add_i32 s9, 0, 0x18000
	v_and_b32_e32 v177, 63, v176
	s_cmp_lg_u32 0, -1
	s_cselect_b32 s10, 0, 0
	s_lshl_b32 s8, s8, 12
	s_mov_b32 s35, 1
	s_mov_b32 s12, 2
	v_cmp_gt_u32_e64 s[38:39], 32, v177
	v_mov_b32_e32 v180, 0
	v_mov_b32_e32 v199, 1.0
	s_waitcnt vmcnt(6)
	ds_write_b128 v99, v[22:25]
	ds_write_b128 v100, v[18:21]
	v_add_co_u32_e32 v18, vcc, s91, v50
	s_waitcnt vmcnt(5)
	ds_write_b128 v195, v[26:29] offset:49152
	s_waitcnt vmcnt(4)
	ds_write_b128 v195, v[30:33] offset:57344
	v_addc_co_u32_e32 v19, vcc, 0, v51, vcc
	v_add_co_u32_e32 v20, vcc, s75, v50
	s_nop 1
	v_addc_co_u32_e32 v21, vcc, 0, v51, vcc
	global_load_dwordx4 v[34:37], v[18:19], off
	global_load_dwordx4 v[38:41], v[20:21], off
	v_add_co_u32_e32 v18, vcc, s91, v48
	s_nop 1
	v_addc_co_u32_e32 v19, vcc, 0, v49, vcc
	v_add_co_u32_e32 v20, vcc, s75, v48
	s_nop 1
	v_addc_co_u32_e32 v21, vcc, 0, v49, vcc
	global_load_dwordx4 v[42:45], v[18:19], off
	global_load_dwordx4 v[52:55], v[20:21], off
	s_waitcnt lgkmcnt(0)
	s_barrier
; #define SWRITE(b, i) do { *(bf16x8*)(V_lds + (b) * SHM_V + vst0) = sr_[i].vs0; *(bf16x8*)(V_lds + (b) * SHM_V + vst1) = sr_[i].vs1; \
;     *(bf16x8*)(K_lds + (b) * SHM_K + kdst0) = sr_[i].ks0; *(bf16x8*)(K_lds + (b) * SHM_K + kdst0 + 32 * KW * 2) = sr_[i].ks1; \
;     if constexpr (KW == 192) *(bf16x8*)(K_lds + (b) * SHM_K + kdst2) = sr_[i].ks2; } while (0)
; #define PSM(X0, X1, MN, AL, FIRST) do { if constexpr (DIFF) partialSM_ps<FIRST>(X0, X1, m_reg, AL, negm); else partialSM<DQK>(X0, X1, m_reg, MN, AL); } while (0)
; #define VM0() asm volatile("s_waitcnt vmcnt(0)" ::: "memory")
; #define WGBAR() asm volatile("s_waitcnt lgkmcnt(0)\n\ts_barrier" ::: "memory")
; template <bool FIRST> __device__ __forceinline__ void partialSM_ps(f32x16& p0, f32x16& p1, float& m_reg, float& alpha, f32x16& negm) {
;   float pmax = p0[0];
; #pragma unroll
;   for (int r = 1; r < 16; ++r) pmax = fmaxf(pmax, p0[r]);
; #pragma unroll
;   for (int r = 0; r < 16; ++r) pmax = fmaxf(pmax, p1[r]);
;   { auto rr = __builtin_amdgcn_permlane32_swap(__float_as_uint(pmax), __float_as_uint(pmax), false, false);
;     pmax = fmaxf(__uint_as_float(rr[0]), __uint_as_float(rr[1])); }
;   alpha = 1.f;
;   if (FIRST || !__builtin_expect(__all(pmax <= THRL), 1)) {
;     const float dl = FIRST ? pmax : fmaxf(pmax, 0.f); m_reg += dl;
; #pragma unroll
;     for (int r = 0; r < 16; ++r) { p0[r] -= dl; p1[r] -= dl; }
;     if (!FIRST) alpha = __builtin_amdgcn_exp2f(-dl);
; #pragma unroll
;     for (int r = 0; r < 16; ++r) negm[r] = -m_reg;
;     asm volatile("" : "+v"(negm));
;   }
; #pragma unroll
;   for (int r = 0; r < 16; ++r) p0[r] = __builtin_amdgcn_exp2f(p0[r]);
; template <int DQK, int KW, bool DIFF, int SDEPTH, int QSP, int NBUF>
; __device__ __forceinline__ void attn_unit(const UnitP& P, char* lds) {
;     ...
;     SLOAD(0, 0); VM0(); SWRITE(0, 0); SLOAD(0, 1); WGBAR();
;     qkt<DQK, KW, QSP>(pA0, pA1, K_lds, kb, qr, qsp, negm); PSM(pA0, pA1, mnA, alA, true);
;     VM0(); SWRITE(1, 0); if (2 < NT) SLOAD(0, 2); WGBAR();
	v_add_u32_e32 v18, 0, v183
	ds_read_b128 v[56:59], v18 offset:49152
	ds_read_b128 v[60:63], v18 offset:57344
	v_or_b32_e32 v18, 32, v164
	v_bitop3_b32 v197, v18, v73, v72 bitop3:0xde
	v_add_u32_e32 v18, 0, v197
	ds_read_b128 v[64:67], v18 offset:49152
	ds_read_b128 v[68:71], v18 offset:57344
	s_waitcnt vmcnt(7) lgkmcnt(0)
	v_mfma_f32_32x32x16_bf16 v[18:33], v[56:59], v[142:145], v[2:17]
	v_or_b32_e32 v56, 64, v164
	v_bitop3_b32 v196, v56, v73, v72 bitop3:0xde
	v_mfma_f32_32x32x16_bf16 v[2:17], v[60:63], v[142:145], v[2:17]
	v_add_u32_e32 v60, 0, v196
	ds_read_b128 v[56:59], v60 offset:49152
	ds_read_b128 v[60:63], v60 offset:57344
	s_waitcnt vmcnt(6)
	v_mfma_f32_32x32x16_bf16 v[18:33], v[64:67], v[138:141], v[18:33]
	v_or_b32_e32 v64, 0x60, v164
	v_bitop3_b32 v198, v64, v73, v72 bitop3:0xde
	v_mfma_f32_32x32x16_bf16 v[2:17], v[68:71], v[138:141], v[2:17]
	v_add_u32_e32 v68, 0, v198
	ds_read_b128 v[64:67], v68 offset:49152
	ds_read_b128 v[68:71], v68 offset:57344
	s_waitcnt vmcnt(5) lgkmcnt(3)
	v_mfma_f32_32x32x16_bf16 v[18:33], v[56:59], v[134:137], v[18:33]
	v_and_b32_e32 v56, 0x3fffffc0, v176
	v_lshl_add_u32 v178, v56, 2, s9
	s_mov_b32 s9, 0
	v_lshl_add_u32 v179, v162, 2, v178
	s_waitcnt lgkmcnt(2)
	v_mfma_f32_32x32x16_bf16 v[2:17], v[60:63], v[134:137], v[2:17]
	s_waitcnt vmcnt(4) lgkmcnt(1)
	v_mfma_f32_32x32x16_bf16 v[18:33], v[64:67], v[130:133], v[18:33]
	s_waitcnt lgkmcnt(0)
	v_mfma_f32_32x32x16_bf16 v[2:17], v[68:71], v[130:133], v[2:17]
	s_nop 9
	v_max_f32_e32 v56, v19, v19
	v_max_f32_e32 v57, v18, v18
	v_max_f32_e32 v56, v57, v56
	v_max3_f32 v56, v56, v20, v21
	v_max3_f32 v56, v56, v22, v23
	v_max3_f32 v56, v56, v24, v25
	v_max3_f32 v56, v56, v26, v27
	v_max3_f32 v56, v56, v28, v29
	v_max3_f32 v56, v56, v30, v31
	v_max3_f32 v56, v56, v32, v33
	v_max3_f32 v56, v56, v2, v3
	v_max3_f32 v56, v56, v4, v5
	v_max3_f32 v56, v56, v6, v7
	v_max3_f32 v56, v56, v8, v9
	v_max3_f32 v56, v56, v10, v11
	v_max3_f32 v56, v56, v12, v13
	v_max3_f32 v56, v56, v14, v15
	v_max3_f32 v56, v56, v16, v17
	v_mov_b32_e32 v57, v56
	s_nop 1
	v_permlane32_swap_b32_e32 v56, v57
	v_max_f32_e32 v57, v57, v57
	v_max_f32_e32 v56, v56, v56
	v_max_f32_e32 v56, v56, v57
	v_add_f32_e32 v182, 0, v56
	v_sub_f32_e32 v96, v16, v56
	v_add_co_u32_e32 v16, vcc, s51, v50
	v_sub_f32_e32 v97, v17, v56
	v_xor_b32_e32 v66, 0x80000000, v182
	v_addc_co_u32_e32 v17, vcc, 0, v51, vcc
	v_sub_f32_e32 v57, v18, v56
	v_mov_b32_e32 v67, v66
	v_mov_b32_e32 v68, v66
	v_mov_b32_e32 v69, v66
	v_mov_b32_e32 v70, v66
	v_mov_b32_e32 v71, v66
	v_mov_b32_e32 v72, v66
	v_mov_b32_e32 v73, v66
	v_mov_b32_e32 v74, v66
	v_mov_b32_e32 v75, v66
	v_mov_b32_e32 v76, v66
	v_mov_b32_e32 v77, v66
	v_mov_b32_e32 v78, v66
	v_mov_b32_e32 v79, v66
	v_mov_b32_e32 v80, v66
	v_mov_b32_e32 v81, v66
	v_add_co_u32_e32 v18, vcc, s52, v50
	v_sub_f32_e32 v58, v19, v56
	s_waitcnt vmcnt(0)
	s_nop 0
	v_addc_co_u32_e32 v19, vcc, 0, v51, vcc
	global_load_dwordx4 v[146:149], v[16:17], off
	global_load_dwordx4 v[150:153], v[18:19], off
	v_add_co_u32_e32 v16, vcc, s51, v48
	v_sub_f32_e32 v20, v20, v56
	s_nop 0
	v_addc_co_u32_e32 v17, vcc, 0, v49, vcc
	v_add_co_u32_e32 v18, vcc, s52, v48
	v_lshlrev_b32_e32 v48, 1, v176
	s_nop 0
	v_addc_co_u32_e32 v19, vcc, 0, v49, vcc
	global_load_dwordx4 v[154:157], v[16:17], off
	global_load_dwordx4 v[158:161], v[18:19], off
	v_lshlrev_b32_e32 v18, 3, v177
	v_and_b32_e32 v19, 0xc0, v98
	v_and_or_b32 v19, v18, 24, v19
	v_and_b32_e32 v48, 32, v48
	v_and_b32_e32 v18, 0x100, v18
	v_or3_b32 v18, v19, v48, v18
	v_add_u32_e32 v181, s10, v18
	s_mul_hi_i32 s10, s36, 0x900000
	s_mul_i32 s36, s36, 0x900000
	s_add_u32 s8, s36, s8
	s_addc_u32 s11, s10, 0
	s_and_b32 s10, s33, 15
	s_lshl_b32 s10, s10, 8
	v_sub_f32_e32 v21, v21, v56
	v_sub_f32_e32 v22, v22, v56
	v_sub_f32_e32 v23, v23, v56
	v_sub_f32_e32 v24, v24, v56
	v_sub_f32_e32 v25, v25, v56
	v_sub_f32_e32 v26, v26, v56
	v_sub_f32_e32 v27, v27, v56
	v_sub_f32_e32 v28, v28, v56
	v_sub_f32_e32 v29, v29, v56
	v_sub_f32_e32 v30, v30, v56
	v_sub_f32_e32 v31, v31, v56
	v_sub_f32_e32 v32, v32, v56
	v_sub_f32_e32 v33, v33, v56
	v_add_u32_e32 v18, 0x10000, v195
	s_or_b32 s8, s8, s10
	v_exp_f32_e32 v219, v57
	v_exp_f32_e32 v221, v58
	v_exp_f32_e32 v217, v20
	v_exp_f32_e32 v220, v21
	v_exp_f32_e32 v215, v22
	v_exp_f32_e32 v218, v23
	v_exp_f32_e32 v214, v24
	v_exp_f32_e32 v216, v25
	v_exp_f32_e32 v211, v26
	v_exp_f32_e32 v213, v27
	v_exp_f32_e32 v209, v28
	v_exp_f32_e32 v212, v29
	v_exp_f32_e32 v207, v30
	v_exp_f32_e32 v210, v31
	v_exp_f32_e32 v206, v32
	v_exp_f32_e32 v208, v33
	s_waitcnt vmcnt(7)
	ds_write_b128 v99, v[34:37] offset:16384
	s_waitcnt vmcnt(6)
	ds_write_b128 v100, v[38:41] offset:16384
	s_waitcnt vmcnt(5)
	ds_write_b128 v18, v[42:45]
	s_waitcnt vmcnt(4)
	ds_write_b128 v18, v[52:55] offset:8192
	s_add_u32 s10, s27, s8
	v_mov_b32_e32 v16, v1
	v_mov_b32_e32 v17, v1
	s_waitcnt lgkmcnt(0)
	s_barrier
	s_addc_u32 s11, s28, s11
	v_sub_f32_e32 v95, v15, v56
	v_sub_f32_e32 v94, v14, v56
	v_sub_f32_e32 v93, v13, v56
	v_sub_f32_e32 v92, v12, v56
	v_sub_f32_e32 v91, v11, v56
	v_sub_f32_e32 v90, v10, v56
	v_sub_f32_e32 v89, v9, v56
	v_sub_f32_e32 v88, v8, v56
	v_sub_f32_e32 v87, v7, v56
	v_sub_f32_e32 v86, v6, v56
	v_sub_f32_e32 v85, v5, v56
	v_sub_f32_e32 v84, v4, v56
	v_sub_f32_e32 v83, v3, v56
	v_sub_f32_e32 v82, v2, v56
	v_mov_b32_e32 v2, v1
	v_mov_b32_e32 v3, v1
	v_mov_b32_e32 v4, v1
	v_mov_b32_e32 v5, v1
	v_mov_b32_e32 v6, v1
	v_mov_b32_e32 v7, v1
	v_mov_b32_e32 v8, v1
	v_mov_b32_e32 v9, v1
	v_mov_b32_e32 v10, v1
	v_mov_b32_e32 v11, v1
	v_mov_b32_e32 v12, v1
	v_mov_b32_e32 v13, v1
	v_mov_b32_e32 v14, v1
	v_mov_b32_e32 v15, v1
	v_lshl_add_u64 v[166:167], s[10:11], 0, v[46:47]
	v_mov_b64_e32 v[64:65], v[16:17]
	v_mov_b64_e32 v[48:49], v[16:17]
	v_mov_b64_e32 v[32:33], v[16:17]
	v_mov_b64_e32 v[62:63], v[14:15]
	v_mov_b64_e32 v[60:61], v[12:13]
	v_mov_b64_e32 v[58:59], v[10:11]
	v_mov_b64_e32 v[56:57], v[8:9]
	v_mov_b64_e32 v[54:55], v[6:7]
	v_mov_b64_e32 v[52:53], v[4:5]
	v_mov_b64_e32 v[50:51], v[2:3]
	v_mov_b64_e32 v[46:47], v[14:15]
	v_mov_b64_e32 v[44:45], v[12:13]
	v_mov_b64_e32 v[42:43], v[10:11]
	v_mov_b64_e32 v[40:41], v[8:9]
	v_mov_b64_e32 v[38:39], v[6:7]
	v_mov_b64_e32 v[36:37], v[4:5]
	v_mov_b64_e32 v[34:35], v[2:3]
	v_mov_b64_e32 v[30:31], v[14:15]
	v_mov_b64_e32 v[28:29], v[12:13]
	v_mov_b64_e32 v[26:27], v[10:11]
	v_mov_b64_e32 v[24:25], v[8:9]
	v_mov_b64_e32 v[22:23], v[6:7]
	v_mov_b64_e32 v[20:21], v[4:5]
	v_mov_b64_e32 v[18:19], v[2:3]
	v_mov_b32_e32 v236, v219
	v_mov_b32_e32 v237, v221
	v_mov_b32_e32 v238, v217
	v_mov_b32_e32 v239, v220
	v_mov_b32_e32 v240, v215
	v_mov_b32_e32 v241, v218
	v_mov_b32_e32 v242, v214
	v_mov_b32_e32 v243, v216
	v_mov_b32_e32 v244, v211
	v_mov_b32_e32 v245, v213
	v_mov_b32_e32 v246, v209
	v_mov_b32_e32 v247, v212
	v_mov_b32_e32 v248, v207
	v_mov_b32_e32 v249, v210
	v_mov_b32_e32 v250, v206
	v_mov_b32_e32 v251, v208
; __device__ __forceinline__ void finishSM(f32x16& p0, f32x16& p1, float alpha, float& l_reg, bf16x8& pa0, bf16x8& pa1, bf16x8& pa2, bf16x8& pa3) {
; #pragma unroll
;   for (int r = 0; r < 16; ++r) p1[r] = __builtin_amdgcn_exp2f(p1[r]);
;   float ps = 0;
; #pragma unroll
;   for (int r = 0; r < 16; ++r) ps += p0[r];
; #pragma unroll
;   for (int r = 0; r < 16; ++r) ps += p1[r];
;   { auto rr = __builtin_amdgcn_permlane32_swap(__float_as_uint(ps), __float_as_uint(ps), false, false);
;     ps = __uint_as_float(rr[0]) + __uint_as_float(rr[1]); }
;   l_reg = l_reg * alpha + ps;
;     ...
;   PK4(p0, 0, pa0); PK4(p0, 8, pa1); PK4(p1, 0, pa2); PK4(p1, 8, pa3);
;     ...
; }
; template <int DQK, int KW, int QSP> __device__ __forceinline__ void qkt(f32x16& p0, f32x16& p1, const char* Ks, const int (&kb)[4], const bf16x8* qr, const char* qsp, const f32x16& cinit) {
;   p0 = cinit; p1 = cinit;
;   constexpr int N = DQK / 16;
;     ...
;   bf16x8 f0[2], f1[2];
;   f0[0] = KRD(0, 1); f1[0] = KRD(0, 0);
; #pragma unroll
;   for (int d0 = 0; d0 < N; ++d0) {
;     if (d0 + 1 < N) { f0[(d0 + 1) & 1] = KRD(d0 + 1, 1); f1[(d0 + 1) & 1] = KRD(d0 + 1, 0); }
;     __builtin_amdgcn_sched_barrier(0x406);
;     bf16x8 qf;
;     if constexpr (QSP > 0) { if (d0 >= N - QSP) qf = *reinterpret_cast<const bf16x8*>(qsp + (d0 - (N - QSP)) * 1024); else qf = qr[d0]; } else qf = qr[d0];
;     p0 = __builtin_amdgcn_mfma_f32_32x32x16_bf16(f0[d0 & 1], qf, p0, 0, 0, 0);
;     p1 = __builtin_amdgcn_mfma_f32_32x32x16_bf16(f1[d0 & 1], qf, p1, 0, 0, 0);
;     __builtin_amdgcn_sched_barrier(0x406); }
.LBB0_316:
	s_lshl_b32 s10, s35, 14
	s_add_i32 s8, s10, 0
	v_add_u32_e32 v102, s8, v183
	ds_read_b128 v[98:101], v102 offset:49152
	v_add_u32_e32 v103, s8, v197
	ds_read_b128 v[200:203], v102 offset:57344
	ds_read_b128 v[222:225], v103 offset:49152
	ds_read_b128 v[226:229], v103 offset:57344
	v_add_u32_e32 v204, s8, v196
	v_exp_f32_e32 v205, v85
	v_exp_f32_e32 v97, v97
	s_waitcnt lgkmcnt(3)
	v_mfma_f32_32x32x16_bf16 v[114:129], v[98:101], v[142:145], v[66:81]
	s_waitcnt lgkmcnt(2)
	v_mfma_f32_32x32x16_bf16 v[98:113], v[200:203], v[142:145], v[66:81]
	ds_read_b128 v[200:203], v204 offset:49152
	ds_read_b128 v[230:233], v204 offset:57344
	v_add_u32_e32 v204, s8, v198
	s_waitcnt lgkmcnt(3)
	v_mfma_f32_32x32x16_bf16 v[114:129], v[222:225], v[138:141], v[114:129]
	s_waitcnt lgkmcnt(2)
	v_mfma_f32_32x32x16_bf16 v[98:113], v[226:229], v[138:141], v[98:113]
	ds_read_b128 v[222:225], v204 offset:49152
	ds_read_b128 v[226:229], v204 offset:57344
	v_exp_f32_e32 v204, v84
	s_waitcnt lgkmcnt(3)
	v_mfma_f32_32x32x16_bf16 v[114:129], v[200:203], v[134:137], v[114:129]
	v_exp_f32_e32 v202, v82
	v_add_f32_e32 v82, 0, v236
	v_add_f32_e32 v82, v237, v82
	v_add_f32_e32 v82, v238, v82
	v_add_f32_e32 v82, v239, v82
	v_add_f32_e32 v82, v240, v82
	v_add_f32_e32 v82, v241, v82
	v_add_f32_e32 v82, v242, v82
	v_add_f32_e32 v82, v243, v82
	v_add_f32_e32 v82, v244, v82
	v_add_f32_e32 v82, v245, v82
	v_add_f32_e32 v82, v246, v82
	v_add_f32_e32 v82, v247, v82
	s_waitcnt lgkmcnt(2)
	v_mfma_f32_32x32x16_bf16 v[98:113], v[230:233], v[134:137], v[98:113]
	v_add_f32_e32 v82, v248, v82
	v_exp_f32_e32 v203, v83
	v_add_f32_e32 v82, v249, v82
	v_add_f32_e32 v82, v250, v82
	v_add_f32_e32 v82, v251, v82
	v_add_f32_e32 v82, v202, v82
	v_add_f32_e32 v82, v203, v82
	s_waitcnt lgkmcnt(1)
	v_mfma_f32_32x32x16_bf16 v[114:129], v[222:225], v[130:133], v[114:129]
	v_exp_f32_e32 v222, v86
	v_exp_f32_e32 v223, v87
	v_exp_f32_e32 v224, v88
	v_add_f32_e32 v82, v204, v82
	v_exp_f32_e32 v225, v89
	v_add_f32_e32 v82, v205, v82
	v_add_f32_e32 v82, v222, v82
	s_waitcnt lgkmcnt(0)
	v_mfma_f32_32x32x16_bf16 v[98:113], v[226:229], v[130:133], v[98:113]
	v_exp_f32_e32 v226, v90
	v_exp_f32_e32 v227, v91
	v_add_f32_e32 v82, v223, v82
	v_exp_f32_e32 v228, v92
	v_add_f32_e32 v82, v224, v82
	v_exp_f32_e32 v229, v93
	v_add_f32_e32 v82, v225, v82
	v_exp_f32_e32 v230, v94
	v_add_f32_e32 v82, v226, v82
	v_exp_f32_e32 v231, v95
	v_add_f32_e32 v82, v227, v82
	v_exp_f32_e32 v232, v96
	v_add_f32_e32 v82, v228, v82
	v_add_f32_e32 v82, v229, v82
	v_add_f32_e32 v82, v230, v82
	v_add_f32_e32 v82, v231, v82
	v_add_f32_e32 v82, v232, v82
	v_add_f32_e32 v200, v97, v82
	v_mov_b32_e32 v201, v200
	v_cvt_pk_bf16_f32 v82, v236, v237
	v_cvt_pk_bf16_f32 v83, v238, v239
	v_cvt_pk_bf16_f32 v84, v240, v241
	s_nop 1
	v_permlane32_swap_b32_e32 v200, v201
	v_cvt_pk_bf16_f32 v85, v242, v243
	v_permlane32_swap_b32_e32 v82, v84
	v_cvt_pk_bf16_f32 v86, v244, v245
	v_cvt_pk_bf16_f32 v87, v246, v247
	v_cvt_pk_bf16_f32 v88, v248, v249
	v_cvt_pk_bf16_f32 v89, v250, v251
	v_cvt_pk_bf16_f32 v90, v202, v203
	v_cvt_pk_bf16_f32 v91, v204, v205
	v_cvt_pk_bf16_f32 v92, v222, v223
	v_cvt_pk_bf16_f32 v93, v224, v225
	v_cvt_pk_bf16_f32 v94, v226, v227
	v_cvt_pk_bf16_f32 v95, v228, v229
	v_cvt_pk_bf16_f32 v96, v230, v231
	v_cvt_pk_bf16_f32 v97, v232, v97
	v_permlane32_swap_b32_e32 v83, v85
	v_permlane32_swap_b32_e32 v86, v88
	v_permlane32_swap_b32_e32 v87, v89
	v_permlane32_swap_b32_e32 v90, v92
	v_permlane32_swap_b32_e32 v91, v93
	v_permlane32_swap_b32_e32 v94, v96
	v_permlane32_swap_b32_e32 v95, v97
	s_lshl_b32 s13, s12, 14
	s_add_i32 s11, s13, 0
	v_add_u32_e32 v202, s11, v192
	s_waitcnt vmcnt(0)
	s_waitcnt vmcnt(3)
	ds_write_b128 v202, v[146:149]
	v_add_u32_e32 v146, s11, v193
	s_waitcnt vmcnt(1)
	ds_write_b128 v146, v[150:153]
	v_add_u32_e32 v146, s11, v194
	s_mov_b32 s8, 0xfffa0000
	s_waitcnt vmcnt(1)
	ds_write_b128 v146, v[154:157] offset:49152
	s_waitcnt vmcnt(0)
; #define SBAR() __builtin_amdgcn_sched_barrier(0)
; template <bool FIRST> __device__ __forceinline__ void partialSM_ps(f32x16& p0, f32x16& p1, float& m_reg, float& alpha, f32x16& negm) {
;   float pmax = p0[0];
; #pragma unroll
;   for (int r = 1; r < 16; ++r) pmax = fmaxf(pmax, p0[r]);
; #pragma unroll
;   for (int r = 0; r < 16; ++r) pmax = fmaxf(pmax, p1[r]);
;   { auto rr = __builtin_amdgcn_permlane32_swap(__float_as_uint(pmax), __float_as_uint(pmax), false, false);
;     pmax = fmaxf(__uint_as_float(rr[0]), __uint_as_float(rr[1])); }
;   alpha = 1.f;
;   if (FIRST || !__builtin_expect(__all(pmax <= THRL), 1)) {
;     const float dl = FIRST ? pmax : fmaxf(pmax, 0.f); m_reg += dl;
; #pragma unroll
;     for (int r = 0; r < 16; ++r) { p0[r] -= dl; p1[r] -= dl; }
;     if (!FIRST) alpha = __builtin_amdgcn_exp2f(-dl);
; #pragma unroll
;     for (int r = 0; r < 16; ++r) negm[r] = -m_reg;
;     asm volatile("" : "+v"(negm));
;   }
; #pragma unroll
;   for (int r = 0; r < 16; ++r) p0[r] = __builtin_amdgcn_exp2f(p0[r]);
; template <int OFF> __device__ __forceinline__ s16x4 tr_read(int vb) {
;   s16x4 r; asm volatile("ds_read_b64_tr_b16 %0, %1 offset:%2" : "=&v"(r) : "v"(vb), "i"(OFF) : "memory"); return r;
; }
; template <int D0> __device__ __forceinline__ void pv_one(f32x16& od, int vb, bf16x8 pa0, bf16x8 pa1, bf16x8 pa2, bf16x8 pa3) {
;   const s16x4 l0 = tr_read<v_rd_off(D0, 0, 0)>(vb), h0 = tr_read<v_rd_off(D0, 0, 1)>(vb), l1 = tr_read<v_rd_off(D0, 1, 0)>(vb), h1 = tr_read<v_rd_off(D0, 1, 1)>(vb);
;   const s16x4 l2 = tr_read<v_rd_off(D0, 2, 0)>(vb), h2 = tr_read<v_rd_off(D0, 2, 1)>(vb), l3 = tr_read<v_rd_off(D0, 3, 0)>(vb), h3 = tr_read<v_rd_off(D0, 3, 1)>(vb);
;   asm volatile("s_waitcnt lgkmcnt(0)" ::: "memory"); SBAR();
;     ...
;   od = __builtin_amdgcn_mfma_f32_32x32x16_bf16(pa0, PK(l0, h0), od, 0, 0, 0);
;   od = __builtin_amdgcn_mfma_f32_32x32x16_bf16(pa1, PK(l1, h1), od, 0, 0, 0);
;   od = __builtin_amdgcn_mfma_f32_32x32x16_bf16(pa2, PK(l2, h2), od, 0, 0, 0);
;   od = __builtin_amdgcn_mfma_f32_32x32x16_bf16(pa3, PK(l3, h3), od, 0, 0, 0);
;     ...
; }
; __device__ __forceinline__ void pv_d0(f32x16* o, int vb, bf16x8 pa0, bf16x8 pa1, bf16x8 pa2, bf16x8 pa3) {
;   pv_one<0>(o[0], vb, pa0, pa1, pa2, pa3); pv_one<1>(o[1], vb, pa0, pa1, pa2, pa3); pv_one<2>(o[2], vb, pa0, pa1, pa2, pa3); pv_one<3>(o[3], vb, pa0, pa1, pa2, pa3);
	ds_write_b128 v146, v[158:161] offset:57344
	v_add_co_u32_e32 v146, vcc, s8, v166
	s_mov_b32 s8, 0xfffc0000
	s_nop 0
	v_addc_co_u32_e32 v147, vcc, -1, v167, vcc
	v_add_co_u32_e32 v150, vcc, s8, v166
	s_mov_b32 s8, 0xfb7a0000
	s_nop 0
	v_addc_co_u32_e32 v151, vcc, -1, v167, vcc
	v_add_co_u32_e32 v154, vcc, s8, v166
	s_mov_b32 s8, 0xfb7c0000
	s_nop 0
	v_addc_co_u32_e32 v155, vcc, -1, v167, vcc
	v_add_co_u32_e32 v158, vcc, s8, v166
	global_load_dwordx4 v[146:149], v[146:147], off
	s_nop 0
	global_load_dwordx4 v[150:153], v[150:151], off
	v_addc_co_u32_e32 v159, vcc, -1, v167, vcc
	global_load_dwordx4 v[154:157], v[154:155], off
	s_nop 0
	global_load_dwordx4 v[158:161], v[158:159], off
	v_lshl_add_u32 v218, s9, 14, v181
	ds_read_b64_tr_b16 v[202:203], v218 offset:0
	ds_read_b64_tr_b16 v[204:205], v218 offset:0x800
	ds_read_b64_tr_b16 v[206:207], v218 offset:0x1000
	ds_read_b64_tr_b16 v[208:209], v218 offset:0x1800
	ds_read_b64_tr_b16 v[210:211], v218 offset:0x2000
	ds_read_b64_tr_b16 v[212:213], v218 offset:0x2800
	ds_read_b64_tr_b16 v[214:215], v218 offset:0x3000
	ds_read_b64_tr_b16 v[216:217], v218 offset:0x3800
	s_waitcnt lgkmcnt(6)
	s_nop 0
	v_mfma_f32_32x32x16_bf16 v[2:17], v[82:85], v[202:205], v[2:17]
	v_exp_f32_e32 v236, v114
	ds_read_b64_tr_b16 v[202:203], v218 offset:0x200
	ds_read_b64_tr_b16 v[204:205], v218 offset:0xa00
	s_waitcnt lgkmcnt(6)
	v_mfma_f32_32x32x16_bf16 v[2:17], v[86:89], v[206:209], v[2:17]
	v_exp_f32_e32 v237, v115
	ds_read_b64_tr_b16 v[206:207], v218 offset:0x1200
	ds_read_b64_tr_b16 v[208:209], v218 offset:0x1a00
	s_waitcnt lgkmcnt(6)
	v_mfma_f32_32x32x16_bf16 v[2:17], v[90:93], v[210:213], v[2:17]
	v_exp_f32_e32 v238, v116
	ds_read_b64_tr_b16 v[210:211], v218 offset:0x2200
	ds_read_b64_tr_b16 v[212:213], v218 offset:0x2a00
	s_waitcnt lgkmcnt(6)
	v_mfma_f32_32x32x16_bf16 v[2:17], v[94:97], v[214:217], v[2:17]
	v_exp_f32_e32 v239, v117
	ds_read_b64_tr_b16 v[214:215], v218 offset:0x3200
	ds_read_b64_tr_b16 v[216:217], v218 offset:0x3a00
	s_waitcnt lgkmcnt(6)
	v_mfma_f32_32x32x16_bf16 v[50:65], v[82:85], v[202:205], v[50:65]
	v_exp_f32_e32 v240, v118
	ds_read_b64_tr_b16 v[202:203], v218 offset:0x400
	ds_read_b64_tr_b16 v[204:205], v218 offset:0xc00
	s_waitcnt lgkmcnt(6)
	v_mfma_f32_32x32x16_bf16 v[50:65], v[86:89], v[206:209], v[50:65]
	v_exp_f32_e32 v241, v119
	ds_read_b64_tr_b16 v[206:207], v218 offset:0x1400
	ds_read_b64_tr_b16 v[208:209], v218 offset:0x1c00
	s_waitcnt lgkmcnt(6)
	v_mfma_f32_32x32x16_bf16 v[50:65], v[90:93], v[210:213], v[50:65]
	v_exp_f32_e32 v242, v120
	ds_read_b64_tr_b16 v[210:211], v218 offset:0x2400
	ds_read_b64_tr_b16 v[212:213], v218 offset:0x2c00
	s_waitcnt lgkmcnt(6)
	v_mfma_f32_32x32x16_bf16 v[50:65], v[94:97], v[214:217], v[50:65]
	v_exp_f32_e32 v243, v121
	ds_read_b64_tr_b16 v[214:215], v218 offset:0x3400
	ds_read_b64_tr_b16 v[216:217], v218 offset:0x3c00
	s_waitcnt lgkmcnt(6)
	v_mfma_f32_32x32x16_bf16 v[34:49], v[82:85], v[202:205], v[34:49]
	v_exp_f32_e32 v244, v122
	ds_read_b64_tr_b16 v[202:203], v218 offset:0x600
	ds_read_b64_tr_b16 v[204:205], v218 offset:0xe00
	s_waitcnt lgkmcnt(6)
	v_mfma_f32_32x32x16_bf16 v[34:49], v[86:89], v[206:209], v[34:49]
	v_exp_f32_e32 v245, v123
	ds_read_b64_tr_b16 v[206:207], v218 offset:0x1600
	ds_read_b64_tr_b16 v[208:209], v218 offset:0x1e00
	s_waitcnt lgkmcnt(6)
	v_mfma_f32_32x32x16_bf16 v[34:49], v[90:93], v[210:213], v[34:49]
	v_exp_f32_e32 v246, v124
	ds_read_b64_tr_b16 v[210:211], v218 offset:0x2600
	ds_read_b64_tr_b16 v[212:213], v218 offset:0x2e00
	s_waitcnt lgkmcnt(6)
	v_mfma_f32_32x32x16_bf16 v[34:49], v[94:97], v[214:217], v[34:49]
	v_exp_f32_e32 v247, v125
	ds_read_b64_tr_b16 v[214:215], v218 offset:0x3600
	ds_read_b64_tr_b16 v[216:217], v218 offset:0x3e00
	s_waitcnt lgkmcnt(6)
	v_mfma_f32_32x32x16_bf16 v[18:33], v[82:85], v[202:205], v[18:33]
	v_exp_f32_e32 v248, v126
	v_max_f32_e32 v82, v115, v115
	v_max_f32_e32 v83, v114, v114
	v_max_f32_e32 v82, v83, v82
	v_max3_f32 v82, v82, v116, v117
	v_max3_f32 v82, v82, v118, v119
	v_max3_f32 v82, v82, v120, v121
	v_max3_f32 v82, v82, v122, v123
	s_waitcnt lgkmcnt(4)
	v_mfma_f32_32x32x16_bf16 v[18:33], v[86:89], v[206:209], v[18:33]
	v_exp_f32_e32 v249, v127
	v_max3_f32 v82, v82, v124, v125
	v_max3_f32 v82, v82, v126, v127
	v_max3_f32 v82, v82, v128, v129
	v_max3_f32 v82, v82, v98, v99
	v_max3_f32 v82, v82, v100, v101
	v_max3_f32 v82, v82, v102, v103
	v_max3_f32 v82, v82, v104, v105
	s_waitcnt lgkmcnt(2)
	v_mfma_f32_32x32x16_bf16 v[18:33], v[90:93], v[210:213], v[18:33]
	v_exp_f32_e32 v250, v128
	v_max3_f32 v82, v82, v106, v107
	v_max3_f32 v82, v82, v108, v109
	v_max3_f32 v82, v82, v110, v111
	v_max3_f32 v82, v82, v112, v113
	v_mov_b32_e32 v83, v82
	s_nop 1
	v_permlane32_swap_b32_e32 v82, v83
	s_waitcnt lgkmcnt(0)
	v_mfma_f32_32x32x16_bf16 v[18:33], v[94:97], v[214:217], v[18:33]
	v_exp_f32_e32 v251, v129
	v_max_f32_e32 v83, v83, v83
	v_max_f32_e32 v82, v82, v82
	v_max_f32_e32 v82, v82, v83
	v_cmp_ge_f32_e32 vcc, s0, v82
	s_cmp_eq_u64 vcc, exec
	s_cbranch_scc0 .LBB0_331
	v_mov_b32_e32 v203, 1.0

; __device__ __forceinline__ void finishSM(f32x16& p0, f32x16& p1, float alpha, float& l_reg, bf16x8& pa0, bf16x8& pa1, bf16x8& pa2, bf16x8& pa3) {
; #pragma unroll
;   for (int r = 0; r < 16; ++r) p1[r] = __builtin_amdgcn_exp2f(p1[r]);
;   float ps = 0;
; #pragma unroll
;   for (int r = 0; r < 16; ++r) ps += p0[r];
; #pragma unroll
;   for (int r = 0; r < 16; ++r) ps += p1[r];
;   { auto rr = __builtin_amdgcn_permlane32_swap(__float_as_uint(ps), __float_as_uint(ps), false, false);
;     ps = __uint_as_float(rr[0]) + __uint_as_float(rr[1]); }
;   l_reg = l_reg * alpha + ps;
;     ...
;   PK4(p0, 0, pa0); PK4(p0, 8, pa1); PK4(p1, 0, pa2); PK4(p1, 8, pa3);
;     ...
; }
; template <int DQK, int KW, int QSP> __device__ __forceinline__ void qkt(f32x16& p0, f32x16& p1, const char* Ks, const int (&kb)[4], const bf16x8* qr, const char* qsp, const f32x16& cinit) {
;   p0 = cinit; p1 = cinit;
;   constexpr int N = DQK / 16;
;     ...
;   bf16x8 f0[2], f1[2];
;   f0[0] = KRD(0, 1); f1[0] = KRD(0, 0);
; #pragma unroll
;   for (int d0 = 0; d0 < N; ++d0) {
;     if (d0 + 1 < N) { f0[(d0 + 1) & 1] = KRD(d0 + 1, 1); f1[(d0 + 1) & 1] = KRD(d0 + 1, 0); }
;     __builtin_amdgcn_sched_barrier(0x406);
;     bf16x8 qf;
;     if constexpr (QSP > 0) { if (d0 >= N - QSP) qf = *reinterpret_cast<const bf16x8*>(qsp + (d0 - (N - QSP)) * 1024); else qf = qr[d0]; } else qf = qr[d0];
;     p0 = __builtin_amdgcn_mfma_f32_32x32x16_bf16(f0[d0 & 1], qf, p0, 0, 0, 0);
;     p1 = __builtin_amdgcn_mfma_f32_32x32x16_bf16(f1[d0 & 1], qf, p1, 0, 0, 0);
;     __builtin_amdgcn_sched_barrier(0x406); }
.LBB0_322:
	s_add_i32 s8, s12, 1
	s_cmp_lg_u32 s12, 2
	s_cselect_b32 s35, s8, 0
	v_add_u32_e32 v86, s11, v183
	ds_read_b128 v[82:85], v86 offset:49152
	v_add_u32_e32 v87, s11, v197
	ds_read_b128 v[204:207], v86 offset:57344
	ds_read_b128 v[208:211], v87 offset:49152
	ds_read_b128 v[212:215], v87 offset:57344
	v_add_u32_e32 v216, s11, v196
	v_exp_f32_e32 v235, v112
	v_exp_f32_e32 v113, v113
	s_waitcnt lgkmcnt(3)
	v_mfma_f32_32x32x16_bf16 v[114:129], v[82:85], v[142:145], v[66:81]
	s_waitcnt lgkmcnt(2)
	v_mfma_f32_32x32x16_bf16 v[82:97], v[204:207], v[142:145], v[66:81]
	ds_read_b128 v[204:207], v216 offset:49152
	ds_read_b128 v[216:219], v216 offset:57344
	s_waitcnt lgkmcnt(3)
	v_mfma_f32_32x32x16_bf16 v[114:129], v[208:211], v[138:141], v[114:129]
	s_waitcnt lgkmcnt(2)
	v_mfma_f32_32x32x16_bf16 v[82:97], v[212:215], v[138:141], v[82:97]
	v_add_u32_e32 v212, s11, v198
	ds_read_b128 v[208:211], v212 offset:49152
	ds_read_b128 v[212:215], v212 offset:57344
	s_waitcnt lgkmcnt(3)
	v_mfma_f32_32x32x16_bf16 v[114:129], v[204:207], v[134:137], v[114:129]
	v_exp_f32_e32 v206, v98
	v_add_f32_e32 v98, 0, v236
	v_add_f32_e32 v98, v237, v98
	v_add_f32_e32 v98, v238, v98
	v_add_f32_e32 v98, v239, v98
	v_add_f32_e32 v98, v240, v98
	v_add_f32_e32 v98, v241, v98
	v_add_f32_e32 v98, v242, v98
	v_add_f32_e32 v98, v243, v98
	v_add_f32_e32 v98, v244, v98
	v_add_f32_e32 v98, v245, v98
	s_waitcnt lgkmcnt(2)
	v_mfma_f32_32x32x16_bf16 v[82:97], v[216:219], v[134:137], v[82:97]
	v_add_f32_e32 v98, v246, v98
	v_add_f32_e32 v98, v247, v98
	v_add_f32_e32 v98, v248, v98
	v_exp_f32_e32 v207, v99
	v_add_f32_e32 v98, v249, v98
	v_add_f32_e32 v98, v250, v98
	v_add_f32_e32 v98, v251, v98
	s_waitcnt lgkmcnt(1)
	v_mfma_f32_32x32x16_bf16 v[114:129], v[208:211], v[130:133], v[114:129]
	v_exp_f32_e32 v208, v100
	v_exp_f32_e32 v209, v101
	v_exp_f32_e32 v210, v102
	v_add_f32_e32 v98, v206, v98
	v_exp_f32_e32 v211, v103
	v_add_f32_e32 v98, v207, v98
	v_add_f32_e32 v98, v208, v98
	s_waitcnt lgkmcnt(0)
	v_mfma_f32_32x32x16_bf16 v[82:97], v[212:215], v[130:133], v[82:97]
	v_exp_f32_e32 v212, v104
	v_exp_f32_e32 v213, v105
	v_add_f32_e32 v98, v209, v98
	v_exp_f32_e32 v214, v106
	v_add_f32_e32 v98, v210, v98
	v_exp_f32_e32 v215, v107
	v_add_f32_e32 v98, v211, v98
	v_exp_f32_e32 v216, v108
	v_add_f32_e32 v98, v212, v98
	v_exp_f32_e32 v217, v109
	v_add_f32_e32 v98, v213, v98
	v_exp_f32_e32 v218, v110
	v_add_f32_e32 v98, v214, v98
	v_exp_f32_e32 v219, v111
	v_add_f32_e32 v98, v215, v98
	v_add_f32_e32 v98, v216, v98
	v_add_f32_e32 v98, v217, v98
	v_add_f32_e32 v98, v218, v98
	v_add_f32_e32 v98, v219, v98
	v_add_f32_e32 v98, v235, v98
	v_add_f32_e32 v204, v113, v98
	v_mov_b32_e32 v205, v204
	v_cvt_pk_bf16_f32 v98, v236, v237
	v_cvt_pk_bf16_f32 v99, v238, v239
	v_cvt_pk_bf16_f32 v100, v240, v241
	v_cvt_pk_bf16_f32 v101, v242, v243
	v_cvt_pk_bf16_f32 v102, v244, v245
	v_cvt_pk_bf16_f32 v103, v246, v247
	v_cvt_pk_bf16_f32 v104, v248, v249
	v_cvt_pk_bf16_f32 v105, v250, v251
	v_cvt_pk_bf16_f32 v106, v206, v207
	v_cvt_pk_bf16_f32 v107, v208, v209
	v_cvt_pk_bf16_f32 v108, v210, v211
	v_cvt_pk_bf16_f32 v109, v212, v213
	v_cvt_pk_bf16_f32 v110, v214, v215
	v_cvt_pk_bf16_f32 v111, v216, v217
	v_cvt_pk_bf16_f32 v112, v218, v219
	v_cvt_pk_bf16_f32 v113, v235, v113
	s_nop 1
	v_permlane32_swap_b32_e32 v204, v205
	v_permlane32_swap_b32_e32 v98, v100
	v_permlane32_swap_b32_e32 v99, v101
	v_permlane32_swap_b32_e32 v102, v104
	v_permlane32_swap_b32_e32 v103, v105
	v_permlane32_swap_b32_e32 v106, v108
	v_permlane32_swap_b32_e32 v107, v109
	v_permlane32_swap_b32_e32 v110, v112
	v_permlane32_swap_b32_e32 v111, v113
	s_lshl_b32 s33, s35, 14
	s_add_i32 s36, s33, 0
	s_waitcnt vmcnt(0)
	v_add_u32_e32 v202, s36, v192
	s_cmp_ge_u32 s30, s31
	s_waitcnt vmcnt(3)
	ds_write_b128 v202, v[146:149]
	v_add_u32_e32 v202, s36, v193
	s_cselect_b64 s[8:9], -1, 0
	s_waitcnt vmcnt(2)
	ds_write_b128 v202, v[150:153]
	v_add_u32_e32 v202, s33, v195
	s_and_b64 vcc, exec, s[8:9]
	s_waitcnt vmcnt(1)
	ds_write_b128 v202, v[154:157] offset:49152
	s_waitcnt vmcnt(0)
	ds_write_b128 v202, v[158:161] offset:57344
	s_cbranch_vccnz .LBB0_324
	v_add_co_u32_e32 v146, vcc, 0xfffe0000, v166
	s_nop 1
	v_addc_co_u32_e32 v147, vcc, -1, v167, vcc
	v_add_co_u32_e32 v150, vcc, 0xfb7e0000, v166
	s_nop 1
	v_addc_co_u32_e32 v151, vcc, -1, v167, vcc
	v_add_co_u32_e32 v158, vcc, 0xfb800000, v166
	global_load_dwordx4 v[146:149], v[146:147], off
	s_nop 0
	global_load_dwordx4 v[154:157], v[150:151], off
	v_addc_co_u32_e32 v159, vcc, -1, v167, vcc
	global_load_dwordx4 v[150:153], v[166:167], off
	s_nop 0
	global_load_dwordx4 v[158:161], v[158:159], off
; #define SBAR() __builtin_amdgcn_sched_barrier(0)
; template <bool FIRST> __device__ __forceinline__ void partialSM_ps(f32x16& p0, f32x16& p1, float& m_reg, float& alpha, f32x16& negm) {
;   float pmax = p0[0];
; #pragma unroll
;   for (int r = 1; r < 16; ++r) pmax = fmaxf(pmax, p0[r]);
; #pragma unroll
;   for (int r = 0; r < 16; ++r) pmax = fmaxf(pmax, p1[r]);
;   { auto rr = __builtin_amdgcn_permlane32_swap(__float_as_uint(pmax), __float_as_uint(pmax), false, false);
;     pmax = fmaxf(__uint_as_float(rr[0]), __uint_as_float(rr[1])); }
;   alpha = 1.f;
;   if (FIRST || !__builtin_expect(__all(pmax <= THRL), 1)) {
; template <int OFF> __device__ __forceinline__ s16x4 tr_read(int vb) {
;   s16x4 r; asm volatile("ds_read_b64_tr_b16 %0, %1 offset:%2" : "=&v"(r) : "v"(vb), "i"(OFF) : "memory"); return r;
; }
; template <int D0> __device__ __forceinline__ void pv_one(f32x16& od, int vb, bf16x8 pa0, bf16x8 pa1, bf16x8 pa2, bf16x8 pa3) {
;   const s16x4 l0 = tr_read<v_rd_off(D0, 0, 0)>(vb), h0 = tr_read<v_rd_off(D0, 0, 1)>(vb), l1 = tr_read<v_rd_off(D0, 1, 0)>(vb), h1 = tr_read<v_rd_off(D0, 1, 1)>(vb);
;   const s16x4 l2 = tr_read<v_rd_off(D0, 2, 0)>(vb), h2 = tr_read<v_rd_off(D0, 2, 1)>(vb), l3 = tr_read<v_rd_off(D0, 3, 0)>(vb), h3 = tr_read<v_rd_off(D0, 3, 1)>(vb);
;   asm volatile("s_waitcnt lgkmcnt(0)" ::: "memory"); SBAR();
;     ...
;   od = __builtin_amdgcn_mfma_f32_32x32x16_bf16(pa0, PK(l0, h0), od, 0, 0, 0);
;   od = __builtin_amdgcn_mfma_f32_32x32x16_bf16(pa1, PK(l1, h1), od, 0, 0, 0);
;   od = __builtin_amdgcn_mfma_f32_32x32x16_bf16(pa2, PK(l2, h2), od, 0, 0, 0);
;   od = __builtin_amdgcn_mfma_f32_32x32x16_bf16(pa3, PK(l3, h3), od, 0, 0, 0);
;     ...
; }
; __device__ __forceinline__ void pv_d0(f32x16* o, int vb, bf16x8 pa0, bf16x8 pa1, bf16x8 pa2, bf16x8 pa3) {
;   pv_one<0>(o[0], vb, pa0, pa1, pa2, pa3); pv_one<1>(o[1], vb, pa0, pa1, pa2, pa3); pv_one<2>(o[2], vb, pa0, pa1, pa2, pa3); pv_one<3>(o[3], vb, pa0, pa1, pa2, pa3);
.LBB0_324:
	v_add_u32_e32 v202, s10, v181
	ds_read_b64_tr_b16 v[206:207], v202 offset:0
	ds_read_b64_tr_b16 v[208:209], v202 offset:0x800
	ds_read_b64_tr_b16 v[210:211], v202 offset:0x1000
	ds_read_b64_tr_b16 v[212:213], v202 offset:0x1800
	ds_read_b64_tr_b16 v[214:215], v202 offset:0x2000
	ds_read_b64_tr_b16 v[216:217], v202 offset:0x2800
	ds_read_b64_tr_b16 v[218:219], v202 offset:0x3000
	ds_read_b64_tr_b16 v[220:221], v202 offset:0x3800
	s_waitcnt lgkmcnt(6)
	s_nop 0
	v_mfma_f32_32x32x16_bf16 v[2:17], v[98:101], v[206:209], v[2:17]
	v_exp_f32_e32 v236, v114
	ds_read_b64_tr_b16 v[206:207], v202 offset:0x200
	ds_read_b64_tr_b16 v[208:209], v202 offset:0xa00
	s_waitcnt lgkmcnt(6)
	v_mfma_f32_32x32x16_bf16 v[2:17], v[102:105], v[210:213], v[2:17]
	v_exp_f32_e32 v237, v115
	ds_read_b64_tr_b16 v[210:211], v202 offset:0x1200
	ds_read_b64_tr_b16 v[212:213], v202 offset:0x1a00
	s_waitcnt lgkmcnt(6)
	v_mfma_f32_32x32x16_bf16 v[2:17], v[106:109], v[214:217], v[2:17]
	v_exp_f32_e32 v238, v116
	ds_read_b64_tr_b16 v[214:215], v202 offset:0x2200
	ds_read_b64_tr_b16 v[216:217], v202 offset:0x2a00
	s_waitcnt lgkmcnt(6)
	v_mfma_f32_32x32x16_bf16 v[2:17], v[110:113], v[218:221], v[2:17]
	v_exp_f32_e32 v239, v117
	ds_read_b64_tr_b16 v[218:219], v202 offset:0x3200
	ds_read_b64_tr_b16 v[220:221], v202 offset:0x3a00
	s_waitcnt lgkmcnt(6)
	v_mfma_f32_32x32x16_bf16 v[50:65], v[98:101], v[206:209], v[50:65]
	v_exp_f32_e32 v240, v118
	ds_read_b64_tr_b16 v[206:207], v202 offset:0x400
	ds_read_b64_tr_b16 v[208:209], v202 offset:0xc00
	s_waitcnt lgkmcnt(6)
	v_mfma_f32_32x32x16_bf16 v[50:65], v[102:105], v[210:213], v[50:65]
	v_exp_f32_e32 v241, v119
	ds_read_b64_tr_b16 v[210:211], v202 offset:0x1400
	ds_read_b64_tr_b16 v[212:213], v202 offset:0x1c00
	s_waitcnt lgkmcnt(6)
	v_mfma_f32_32x32x16_bf16 v[50:65], v[106:109], v[214:217], v[50:65]
	v_exp_f32_e32 v242, v120
	ds_read_b64_tr_b16 v[214:215], v202 offset:0x2400
	ds_read_b64_tr_b16 v[216:217], v202 offset:0x2c00
	s_waitcnt lgkmcnt(6)
	v_mfma_f32_32x32x16_bf16 v[50:65], v[110:113], v[218:221], v[50:65]
	v_exp_f32_e32 v243, v121
	ds_read_b64_tr_b16 v[218:219], v202 offset:0x3400
	ds_read_b64_tr_b16 v[220:221], v202 offset:0x3c00
	s_waitcnt lgkmcnt(6)
	v_mfma_f32_32x32x16_bf16 v[34:49], v[98:101], v[206:209], v[34:49]
	v_exp_f32_e32 v244, v122
	ds_read_b64_tr_b16 v[206:207], v202 offset:0x600
	ds_read_b64_tr_b16 v[208:209], v202 offset:0xe00
	s_waitcnt lgkmcnt(6)
	v_mfma_f32_32x32x16_bf16 v[34:49], v[102:105], v[210:213], v[34:49]
	v_exp_f32_e32 v245, v123
	ds_read_b64_tr_b16 v[210:211], v202 offset:0x1600
	ds_read_b64_tr_b16 v[212:213], v202 offset:0x1e00
	s_waitcnt lgkmcnt(6)
	v_mfma_f32_32x32x16_bf16 v[34:49], v[106:109], v[214:217], v[34:49]
	v_exp_f32_e32 v246, v124
	ds_read_b64_tr_b16 v[214:215], v202 offset:0x2600
	ds_read_b64_tr_b16 v[216:217], v202 offset:0x2e00
	s_waitcnt lgkmcnt(6)
	v_mfma_f32_32x32x16_bf16 v[34:49], v[110:113], v[218:221], v[34:49]
	v_exp_f32_e32 v247, v125
	ds_read_b64_tr_b16 v[218:219], v202 offset:0x3600
	ds_read_b64_tr_b16 v[220:221], v202 offset:0x3e00
	s_waitcnt lgkmcnt(6)
	v_mfma_f32_32x32x16_bf16 v[18:33], v[98:101], v[206:209], v[18:33]
	v_exp_f32_e32 v248, v126
	v_max_f32_e32 v98, v115, v115
	v_max_f32_e32 v99, v114, v114
	v_max_f32_e32 v98, v99, v98
	v_max3_f32 v98, v98, v116, v117
	v_max3_f32 v98, v98, v118, v119
	v_max3_f32 v98, v98, v120, v121
	v_max3_f32 v98, v98, v122, v123
	s_waitcnt lgkmcnt(4)
	v_mfma_f32_32x32x16_bf16 v[18:33], v[102:105], v[210:213], v[18:33]
	v_exp_f32_e32 v249, v127
	v_max3_f32 v98, v98, v124, v125
	v_max3_f32 v98, v98, v126, v127
	v_max3_f32 v98, v98, v128, v129
	v_max3_f32 v98, v98, v82, v83
	v_max3_f32 v98, v98, v84, v85
	v_max3_f32 v98, v98, v86, v87
	v_max3_f32 v98, v98, v88, v89
	s_waitcnt lgkmcnt(2)
	v_mfma_f32_32x32x16_bf16 v[18:33], v[106:109], v[214:217], v[18:33]
	v_exp_f32_e32 v250, v128
	v_max3_f32 v98, v98, v90, v91
	v_max3_f32 v98, v98, v92, v93
	v_max3_f32 v98, v98, v94, v95
	v_max3_f32 v98, v98, v96, v97
	v_mov_b32_e32 v99, v98
	s_nop 1
	v_permlane32_swap_b32_e32 v98, v99
	s_waitcnt lgkmcnt(0)
	v_mfma_f32_32x32x16_bf16 v[18:33], v[110:113], v[218:221], v[18:33]
	v_exp_f32_e32 v251, v129
	v_max_f32_e32 v99, v99, v99
	v_max_f32_e32 v98, v98, v98
	v_max_f32_e32 v98, v98, v99
	v_cmp_ge_f32_e32 vcc, s0, v98
	s_cmp_eq_u64 vcc, exec
	v_mov_b32_e32 v202, 1.0
	s_cbranch_scc0 .LBB0_332

; template <bool FIRST> __device__ __forceinline__ void partialSM_ps(f32x16& p0, f32x16& p1, float& m_reg, float& alpha, f32x16& negm) {
;     ...
;   if (FIRST || !__builtin_expect(__all(pmax <= THRL), 1)) {
;     const float dl = FIRST ? pmax : fmaxf(pmax, 0.f); m_reg += dl;
; #pragma unroll
;     for (int r = 0; r < 16; ++r) { p0[r] -= dl; p1[r] -= dl; }
;     if (!FIRST) alpha = __builtin_amdgcn_exp2f(-dl);
; #pragma unroll
;     for (int r = 0; r < 16; ++r) negm[r] = -m_reg;
;     asm volatile("" : "+v"(negm));
;   }
; #pragma unroll
;   for (int r = 0; r < 16; ++r) p0[r] = __builtin_amdgcn_exp2f(p0[r]);
.LBB0_331:
	v_max_f32_e32 v66, v82, v82
	v_max_f32_e32 v66, 0, v66
	v_exp_f32_e64 v203, -v66
	v_add_f32_e32 v182, v182, v66
	v_pk_add_f32 v[114:115], v[114:115], v[66:67] op_sel_hi:[1,0] neg_lo:[0,1] neg_hi:[0,1]
	v_pk_add_f32 v[116:117], v[116:117], v[66:67] op_sel_hi:[1,0] neg_lo:[0,1] neg_hi:[0,1]
	v_pk_add_f32 v[118:119], v[118:119], v[66:67] op_sel_hi:[1,0] neg_lo:[0,1] neg_hi:[0,1]
	v_pk_add_f32 v[120:121], v[120:121], v[66:67] op_sel_hi:[1,0] neg_lo:[0,1] neg_hi:[0,1]
	v_pk_add_f32 v[122:123], v[122:123], v[66:67] op_sel_hi:[1,0] neg_lo:[0,1] neg_hi:[0,1]
	v_pk_add_f32 v[124:125], v[124:125], v[66:67] op_sel_hi:[1,0] neg_lo:[0,1] neg_hi:[0,1]
	v_pk_add_f32 v[126:127], v[126:127], v[66:67] op_sel_hi:[1,0] neg_lo:[0,1] neg_hi:[0,1]
	v_pk_add_f32 v[128:129], v[128:129], v[66:67] op_sel_hi:[1,0] neg_lo:[0,1] neg_hi:[0,1]
	v_sub_f32_e32 v113, v113, v66
	v_sub_f32_e32 v112, v112, v66
	v_sub_f32_e32 v111, v111, v66
	v_sub_f32_e32 v110, v110, v66
	v_sub_f32_e32 v109, v109, v66
	v_sub_f32_e32 v108, v108, v66
	v_sub_f32_e32 v107, v107, v66
	v_sub_f32_e32 v106, v106, v66
	v_sub_f32_e32 v105, v105, v66
	v_sub_f32_e32 v104, v104, v66
	v_sub_f32_e32 v103, v103, v66
	v_sub_f32_e32 v102, v102, v66
	v_sub_f32_e32 v101, v101, v66
	v_sub_f32_e32 v100, v100, v66
	v_sub_f32_e32 v99, v99, v66
	v_sub_f32_e32 v98, v98, v66
	v_xor_b32_e32 v66, 0x80000000, v182
	v_mov_b32_e32 v67, v66
	v_mov_b32_e32 v68, v66
	v_mov_b32_e32 v69, v66
	v_mov_b32_e32 v70, v66
	v_mov_b32_e32 v71, v66
	v_mov_b32_e32 v72, v66
	v_mov_b32_e32 v73, v66
	v_mov_b32_e32 v74, v66
	v_mov_b32_e32 v75, v66
	v_mov_b32_e32 v76, v66
	v_mov_b32_e32 v77, v66
	v_mov_b32_e32 v78, v66
	v_mov_b32_e32 v79, v66
	v_mov_b32_e32 v80, v66
	v_mov_b32_e32 v81, v66
	v_exp_f32_e32 v236, v114
	v_exp_f32_e32 v237, v115
	v_exp_f32_e32 v238, v116
	v_exp_f32_e32 v239, v117
	v_exp_f32_e32 v240, v118
	v_exp_f32_e32 v241, v119
	v_exp_f32_e32 v242, v120
	v_exp_f32_e32 v243, v121
	v_exp_f32_e32 v244, v122
	v_exp_f32_e32 v245, v123
	v_exp_f32_e32 v246, v124
	v_exp_f32_e32 v247, v125
	v_exp_f32_e32 v248, v126
	v_exp_f32_e32 v249, v127
	v_exp_f32_e32 v250, v128
	v_exp_f32_e32 v251, v129
	s_branch .LBB0_318
.LBB0_332:
	v_max_f32_e32 v66, v98, v98
	v_max_f32_e32 v66, 0, v66
	v_exp_f32_e64 v202, -v66
	v_add_f32_e32 v182, v182, v66
	v_pk_add_f32 v[114:115], v[114:115], v[66:67] op_sel_hi:[1,0] neg_lo:[0,1] neg_hi:[0,1]
	v_pk_add_f32 v[116:117], v[116:117], v[66:67] op_sel_hi:[1,0] neg_lo:[0,1] neg_hi:[0,1]
	v_pk_add_f32 v[118:119], v[118:119], v[66:67] op_sel_hi:[1,0] neg_lo:[0,1] neg_hi:[0,1]
	v_pk_add_f32 v[120:121], v[120:121], v[66:67] op_sel_hi:[1,0] neg_lo:[0,1] neg_hi:[0,1]
	v_pk_add_f32 v[122:123], v[122:123], v[66:67] op_sel_hi:[1,0] neg_lo:[0,1] neg_hi:[0,1]
	v_pk_add_f32 v[124:125], v[124:125], v[66:67] op_sel_hi:[1,0] neg_lo:[0,1] neg_hi:[0,1]
	v_pk_add_f32 v[126:127], v[126:127], v[66:67] op_sel_hi:[1,0] neg_lo:[0,1] neg_hi:[0,1]
	v_pk_add_f32 v[128:129], v[128:129], v[66:67] op_sel_hi:[1,0] neg_lo:[0,1] neg_hi:[0,1]
	v_sub_f32_e32 v97, v97, v66
	v_sub_f32_e32 v96, v96, v66
	v_sub_f32_e32 v95, v95, v66
	v_sub_f32_e32 v94, v94, v66
	v_sub_f32_e32 v93, v93, v66
	v_sub_f32_e32 v92, v92, v66
	v_sub_f32_e32 v91, v91, v66
	v_sub_f32_e32 v90, v90, v66
	v_sub_f32_e32 v89, v89, v66
	v_sub_f32_e32 v88, v88, v66
	v_sub_f32_e32 v87, v87, v66
	v_sub_f32_e32 v86, v86, v66
	v_sub_f32_e32 v85, v85, v66
	v_sub_f32_e32 v84, v84, v66
	v_sub_f32_e32 v83, v83, v66
	v_sub_f32_e32 v82, v82, v66
	v_xor_b32_e32 v66, 0x80000000, v182
	v_mov_b32_e32 v67, v66
	v_mov_b32_e32 v68, v66
	v_mov_b32_e32 v69, v66
	v_mov_b32_e32 v70, v66
	v_mov_b32_e32 v71, v66
	v_mov_b32_e32 v72, v66
	v_mov_b32_e32 v73, v66
	v_mov_b32_e32 v74, v66
	v_mov_b32_e32 v75, v66
	v_mov_b32_e32 v76, v66
	v_mov_b32_e32 v77, v66
	v_mov_b32_e32 v78, v66
	v_mov_b32_e32 v79, v66
	v_mov_b32_e32 v80, v66
	v_mov_b32_e32 v81, v66
	v_exp_f32_e32 v236, v114
	v_exp_f32_e32 v237, v115
	v_exp_f32_e32 v238, v116
	v_exp_f32_e32 v239, v117
	v_exp_f32_e32 v240, v118
	v_exp_f32_e32 v241, v119
	v_exp_f32_e32 v242, v120
	v_exp_f32_e32 v243, v121
	v_exp_f32_e32 v244, v122
	v_exp_f32_e32 v245, v123
	v_exp_f32_e32 v246, v124
	v_exp_f32_e32 v247, v125
	v_exp_f32_e32 v248, v126
	v_exp_f32_e32 v249, v127
	v_exp_f32_e32 v250, v128
	v_exp_f32_e32 v251, v129
	s_branch .LBB0_325
; #define SBAR() __builtin_amdgcn_sched_barrier(0)
; #define SWRITE(b, i) do { *(bf16x8*)(V_lds + (b) * SHM_V + vst0) = sr_[i].vs0; *(bf16x8*)(V_lds + (b) * SHM_V + vst1) = sr_[i].vs1; \
;     *(bf16x8*)(K_lds + (b) * SHM_K + kdst0) = sr_[i].ks0; *(bf16x8*)(K_lds + (b) * SHM_K + kdst0 + 32 * KW * 2) = sr_[i].ks1; \
;     if constexpr (KW == 192) *(bf16x8*)(K_lds + (b) * SHM_K + kdst2) = sr_[i].ks2; } while (0)
; #define PSM(X0, X1, MN, AL, FIRST) do { if constexpr (DIFF) partialSM_ps<FIRST>(X0, X1, m_reg, AL, negm); else partialSM<DQK>(X0, X1, m_reg, MN, AL); } while (0)
; #define VM0() asm volatile("s_waitcnt vmcnt(0)" ::: "memory")
; #define WGBAR() asm volatile("s_waitcnt lgkmcnt(0)\n\ts_barrier" ::: "memory")
; __device__ __forceinline__ void finishSM(f32x16& p0, f32x16& p1, float alpha, float& l_reg, bf16x8& pa0, bf16x8& pa1, bf16x8& pa2, bf16x8& pa3) {
; #pragma unroll
;   for (int r = 0; r < 16; ++r) p1[r] = __builtin_amdgcn_exp2f(p1[r]);
;   float ps = 0;
; #pragma unroll
;   for (int r = 0; r < 16; ++r) ps += p0[r];
; #pragma unroll
;   for (int r = 0; r < 16; ++r) ps += p1[r];
;   { auto rr = __builtin_amdgcn_permlane32_swap(__float_as_uint(ps), __float_as_uint(ps), false, false);
;     ps = __uint_as_float(rr[0]) + __uint_as_float(rr[1]); }
;   l_reg = l_reg * alpha + ps;
;     ...
;   PK4(p0, 0, pa0); PK4(p0, 8, pa1); PK4(p1, 0, pa2); PK4(p1, 8, pa3);
; template <int DQK, int KW, bool DIFF, int SDEPTH, int QSP, int NBUF>
; __device__ __forceinline__ void attn_unit(const UnitP& P, char* lds) {
;     ...
;     int rprev = 0, rcur = 1, rnext = 2;
;     SLOAD(0, 0); VM0(); SWRITE(0, 0); SLOAD(0, 1); WGBAR();
;     qkt<DQK, KW, QSP>(pA0, pA1, K_lds, kb, qr, qsp, negm); PSM(pA0, pA1, mnA, alA, true);
;     VM0(); SWRITE(1, 0); if (2 < NT) SLOAD(0, 2); WGBAR();
;     for (int j = 1; j + 1 < NT; j += 2) {
;       RSTEP(pB0, pB1, mnB, alB, pA0, pA1, alA, true, true, j + 2);
;       RSTEP(pA0, pA1, mnA, alA, pB0, pB1, alB, true, (j + 3 < NT), j + 3);
;     }
;     RSTEP(pB0, pB1, mnB, alB, pA0, pA1, alA, false, false, 0);
;     finishSM(pB0, pB1, alB, l_reg, pa0, pa1, pa2, pa3); SBAR();
.LBB0_333:
	v_mov_b32_e32 v219, v236
	v_mov_b32_e32 v221, v237
	v_mov_b32_e32 v217, v238
	v_mov_b32_e32 v220, v239
	v_mov_b32_e32 v215, v240
	v_mov_b32_e32 v218, v241
	v_mov_b32_e32 v214, v242
	v_mov_b32_e32 v216, v243
	v_mov_b32_e32 v211, v244
	v_mov_b32_e32 v213, v245
	v_mov_b32_e32 v209, v246
	v_mov_b32_e32 v212, v247
	v_mov_b32_e32 v207, v248
	v_mov_b32_e32 v210, v249
	v_mov_b32_e32 v206, v250
	v_mov_b32_e32 v208, v251
	v_add_u32_e32 v98, s36, v183
	ds_read_b128 v[114:117], v98 offset:49152
	v_add_u32_e32 v99, s36, v197
	ds_read_b128 v[118:121], v98 offset:57344
	ds_read_b128 v[122:125], v99 offset:49152
	ds_read_b128 v[126:129], v99 offset:57344
	v_exp_f32_e32 v97, v97
	s_waitcnt lgkmcnt(3)
	v_mfma_f32_32x32x16_bf16 v[98:113], v[114:117], v[142:145], v[66:81]
	s_waitcnt lgkmcnt(2)
	v_mfma_f32_32x32x16_bf16 v[66:81], v[118:121], v[142:145], v[66:81]
	v_add_u32_e32 v118, s36, v196
	ds_read_b128 v[114:117], v118 offset:49152
	ds_read_b128 v[118:121], v118 offset:57344
	s_waitcnt lgkmcnt(3)
	v_mfma_f32_32x32x16_bf16 v[98:113], v[122:125], v[138:141], v[98:113]
	s_waitcnt lgkmcnt(2)
	v_mfma_f32_32x32x16_bf16 v[66:81], v[126:129], v[138:141], v[66:81]
	v_add_u32_e32 v126, s36, v198
	ds_read_b128 v[122:125], v126 offset:49152
	ds_read_b128 v[126:129], v126 offset:57344
	s_waitcnt lgkmcnt(3)
	v_mfma_f32_32x32x16_bf16 v[98:113], v[114:117], v[134:137], v[98:113]
	v_exp_f32_e32 v116, v82
	v_add_f32_e32 v82, 0, v219
	v_add_f32_e32 v82, v221, v82
	v_add_f32_e32 v82, v217, v82
	v_add_f32_e32 v82, v220, v82
	v_add_f32_e32 v82, v215, v82
	v_add_f32_e32 v82, v218, v82
	v_add_f32_e32 v82, v214, v82
	v_add_f32_e32 v82, v216, v82
	v_add_f32_e32 v82, v211, v82
	v_add_f32_e32 v82, v213, v82
	v_add_f32_e32 v82, v209, v82
	v_add_f32_e32 v82, v212, v82
	v_add_f32_e32 v82, v207, v82
	v_exp_f32_e32 v117, v83
	v_add_f32_e32 v82, v210, v82
	s_waitcnt lgkmcnt(2)
	v_mfma_f32_32x32x16_bf16 v[66:81], v[118:121], v[134:137], v[66:81]
	v_exp_f32_e32 v118, v84
	v_add_f32_e32 v82, v206, v82
	v_exp_f32_e32 v119, v85
	v_add_f32_e32 v82, v208, v82
	v_exp_f32_e32 v120, v86
	v_add_f32_e32 v82, v116, v82
	v_exp_f32_e32 v121, v87
	v_add_f32_e32 v82, v117, v82
	s_waitcnt lgkmcnt(1)
	v_mfma_f32_32x32x16_bf16 v[98:113], v[122:125], v[130:133], v[98:113]
	v_exp_f32_e32 v122, v88
	v_add_f32_e32 v82, v118, v82
	v_exp_f32_e32 v123, v89
	v_add_f32_e32 v82, v119, v82
	v_exp_f32_e32 v124, v90
	v_add_f32_e32 v82, v120, v82
	v_exp_f32_e32 v125, v91
	v_add_f32_e32 v82, v121, v82
	s_waitcnt lgkmcnt(0)
	v_mfma_f32_32x32x16_bf16 v[66:81], v[126:129], v[130:133], v[66:81]
	v_exp_f32_e32 v126, v92
	v_add_f32_e32 v82, v122, v82
	v_exp_f32_e32 v127, v93
	v_add_f32_e32 v82, v123, v82
	v_exp_f32_e32 v128, v94
	v_add_f32_e32 v82, v124, v82
	v_exp_f32_e32 v129, v95
	v_add_f32_e32 v82, v125, v82
	v_exp_f32_e32 v130, v96
	v_add_f32_e32 v82, v126, v82
	v_add_f32_e32 v82, v127, v82
	v_add_f32_e32 v82, v128, v82
	v_add_f32_e32 v82, v129, v82
	v_add_f32_e32 v82, v130, v82
	v_add_f32_e32 v114, v97, v82
	v_mov_b32_e32 v115, v114
	v_cvt_pk_bf16_f32 v82, v219, v221
	v_cvt_pk_bf16_f32 v83, v217, v220
	v_cvt_pk_bf16_f32 v84, v215, v218
	s_nop 1
	v_permlane32_swap_b32_e32 v114, v115
	v_cvt_pk_bf16_f32 v85, v214, v216
	v_permlane32_swap_b32_e32 v82, v84
	v_cvt_pk_bf16_f32 v86, v211, v213
	v_cvt_pk_bf16_f32 v87, v209, v212
	v_cvt_pk_bf16_f32 v88, v207, v210
	v_cvt_pk_bf16_f32 v89, v206, v208
	v_cvt_pk_bf16_f32 v90, v116, v117
	v_cvt_pk_bf16_f32 v91, v118, v119
	v_cvt_pk_bf16_f32 v92, v120, v121
	v_cvt_pk_bf16_f32 v93, v122, v123
	v_cvt_pk_bf16_f32 v94, v124, v125
	v_cvt_pk_bf16_f32 v95, v126, v127
	v_cvt_pk_bf16_f32 v96, v128, v129
	v_cvt_pk_bf16_f32 v97, v130, v97
	v_permlane32_swap_b32_e32 v83, v85
	v_permlane32_swap_b32_e32 v86, v88
	v_permlane32_swap_b32_e32 v87, v89
	v_permlane32_swap_b32_e32 v90, v92
	v_permlane32_swap_b32_e32 v91, v93
	v_permlane32_swap_b32_e32 v94, v96
	v_permlane32_swap_b32_e32 v95, v97
	v_add_u32_e32 v132, s13, v181
	ds_read_b64_tr_b16 v[116:117], v132 offset:0
	ds_read_b64_tr_b16 v[118:119], v132 offset:0x800
	ds_read_b64_tr_b16 v[120:121], v132 offset:0x1000
	ds_read_b64_tr_b16 v[122:123], v132 offset:0x1800
	ds_read_b64_tr_b16 v[124:125], v132 offset:0x2000
	ds_read_b64_tr_b16 v[126:127], v132 offset:0x2800
	ds_read_b64_tr_b16 v[128:129], v132 offset:0x3000
	ds_read_b64_tr_b16 v[130:131], v132 offset:0x3800
	s_waitcnt lgkmcnt(0)
; #define SBAR() __builtin_amdgcn_sched_barrier(0)
; template <bool FIRST> __device__ __forceinline__ void partialSM_ps(f32x16& p0, f32x16& p1, float& m_reg, float& alpha, f32x16& negm) {
;   float pmax = p0[0];
; #pragma unroll
;   for (int r = 1; r < 16; ++r) pmax = fmaxf(pmax, p0[r]);
; #pragma unroll
;   for (int r = 0; r < 16; ++r) pmax = fmaxf(pmax, p1[r]);
;   { auto rr = __builtin_amdgcn_permlane32_swap(__float_as_uint(pmax), __float_as_uint(pmax), false, false);
;     pmax = fmaxf(__uint_as_float(rr[0]), __uint_as_float(rr[1])); }
;   alpha = 1.f;
;   if (FIRST || !__builtin_expect(__all(pmax <= THRL), 1)) {
; template <int OFF> __device__ __forceinline__ s16x4 tr_read(int vb) {
;   s16x4 r; asm volatile("ds_read_b64_tr_b16 %0, %1 offset:%2" : "=&v"(r) : "v"(vb), "i"(OFF) : "memory"); return r;
; }
; template <int D0> __device__ __forceinline__ void pv_one(f32x16& od, int vb, bf16x8 pa0, bf16x8 pa1, bf16x8 pa2, bf16x8 pa3) {
;   const s16x4 l0 = tr_read<v_rd_off(D0, 0, 0)>(vb), h0 = tr_read<v_rd_off(D0, 0, 1)>(vb), l1 = tr_read<v_rd_off(D0, 1, 0)>(vb), h1 = tr_read<v_rd_off(D0, 1, 1)>(vb);
;   const s16x4 l2 = tr_read<v_rd_off(D0, 2, 0)>(vb), h2 = tr_read<v_rd_off(D0, 2, 1)>(vb), l3 = tr_read<v_rd_off(D0, 3, 0)>(vb), h3 = tr_read<v_rd_off(D0, 3, 1)>(vb);
;   asm volatile("s_waitcnt lgkmcnt(0)" ::: "memory"); SBAR();
;     ...
;   od = __builtin_amdgcn_mfma_f32_32x32x16_bf16(pa0, PK(l0, h0), od, 0, 0, 0);
;   od = __builtin_amdgcn_mfma_f32_32x32x16_bf16(pa1, PK(l1, h1), od, 0, 0, 0);
;   od = __builtin_amdgcn_mfma_f32_32x32x16_bf16(pa2, PK(l2, h2), od, 0, 0, 0);
;   od = __builtin_amdgcn_mfma_f32_32x32x16_bf16(pa3, PK(l3, h3), od, 0, 0, 0);
;     ...
; }
; __device__ __forceinline__ void pv_d0(f32x16* o, int vb, bf16x8 pa0, bf16x8 pa1, bf16x8 pa2, bf16x8 pa3) {
;   pv_one<0>(o[0], vb, pa0, pa1, pa2, pa3); pv_one<1>(o[1], vb, pa0, pa1, pa2, pa3); pv_one<2>(o[2], vb, pa0, pa1, pa2, pa3); pv_one<3>(o[3], vb, pa0, pa1, pa2, pa3);
	s_nop 0
	v_mfma_f32_32x32x16_bf16 v[2:17], v[82:85], v[116:119], v[2:17]
	ds_read_b64_tr_b16 v[116:117], v132 offset:0x200
	ds_read_b64_tr_b16 v[118:119], v132 offset:0xa00
	v_mfma_f32_32x32x16_bf16 v[2:17], v[86:89], v[120:123], v[2:17]
	ds_read_b64_tr_b16 v[120:121], v132 offset:0x1200
	ds_read_b64_tr_b16 v[122:123], v132 offset:0x1a00
	v_mfma_f32_32x32x16_bf16 v[2:17], v[90:93], v[124:127], v[2:17]
	ds_read_b64_tr_b16 v[124:125], v132 offset:0x2200
	ds_read_b64_tr_b16 v[126:127], v132 offset:0x2a00
	v_mfma_f32_32x32x16_bf16 v[2:17], v[94:97], v[128:131], v[2:17]
	ds_read_b64_tr_b16 v[128:129], v132 offset:0x3200
	ds_read_b64_tr_b16 v[130:131], v132 offset:0x3a00
	s_waitcnt lgkmcnt(0)
	v_mfma_f32_32x32x16_bf16 v[50:65], v[82:85], v[116:119], v[50:65]
	ds_read_b64_tr_b16 v[116:117], v132 offset:0x400
	ds_read_b64_tr_b16 v[118:119], v132 offset:0xc00
	v_mfma_f32_32x32x16_bf16 v[50:65], v[86:89], v[120:123], v[50:65]
	ds_read_b64_tr_b16 v[120:121], v132 offset:0x1400
	ds_read_b64_tr_b16 v[122:123], v132 offset:0x1c00
	v_mfma_f32_32x32x16_bf16 v[50:65], v[90:93], v[124:127], v[50:65]
	ds_read_b64_tr_b16 v[124:125], v132 offset:0x2400
	ds_read_b64_tr_b16 v[126:127], v132 offset:0x2c00
	v_mfma_f32_32x32x16_bf16 v[50:65], v[94:97], v[128:131], v[50:65]
	ds_read_b64_tr_b16 v[128:129], v132 offset:0x3400
	ds_read_b64_tr_b16 v[130:131], v132 offset:0x3c00
	s_waitcnt lgkmcnt(0)
	v_mfma_f32_32x32x16_bf16 v[34:49], v[82:85], v[116:119], v[34:49]
	ds_read_b64_tr_b16 v[116:117], v132 offset:0x600
	ds_read_b64_tr_b16 v[118:119], v132 offset:0xe00
	v_mfma_f32_32x32x16_bf16 v[34:49], v[86:89], v[120:123], v[34:49]
	ds_read_b64_tr_b16 v[120:121], v132 offset:0x1600
	ds_read_b64_tr_b16 v[122:123], v132 offset:0x1e00
	v_mfma_f32_32x32x16_bf16 v[34:49], v[90:93], v[124:127], v[34:49]
	ds_read_b64_tr_b16 v[124:125], v132 offset:0x2600
	ds_read_b64_tr_b16 v[126:127], v132 offset:0x2e00
	v_mfma_f32_32x32x16_bf16 v[34:49], v[94:97], v[128:131], v[34:49]
	ds_read_b64_tr_b16 v[128:129], v132 offset:0x3600
	ds_read_b64_tr_b16 v[130:131], v132 offset:0x3e00
	s_waitcnt lgkmcnt(0)
	v_mfma_f32_32x32x16_bf16 v[18:33], v[82:85], v[116:119], v[18:33]
	v_max_f32_e32 v82, v99, v99
	v_max_f32_e32 v83, v98, v98
	v_max_f32_e32 v82, v83, v82
	v_max3_f32 v82, v82, v100, v101
	v_max3_f32 v82, v82, v102, v103
	v_max3_f32 v82, v82, v104, v105
	v_max3_f32 v82, v82, v106, v107
	v_mfma_f32_32x32x16_bf16 v[18:33], v[86:89], v[120:123], v[18:33]
	v_max3_f32 v82, v82, v108, v109
	v_max3_f32 v82, v82, v110, v111
	v_max3_f32 v82, v82, v112, v113
	v_max3_f32 v82, v82, v66, v67
	v_max3_f32 v82, v82, v68, v69
	v_max3_f32 v82, v82, v70, v71
	v_max3_f32 v82, v82, v72, v73
	v_mfma_f32_32x32x16_bf16 v[18:33], v[90:93], v[124:127], v[18:33]
	v_max3_f32 v82, v82, v74, v75
	v_max3_f32 v82, v82, v76, v77
	v_max3_f32 v82, v82, v78, v79
	v_max3_f32 v82, v82, v80, v81
	v_mov_b32_e32 v83, v82
	s_nop 1
	v_permlane32_swap_b32_e32 v82, v83
	v_mfma_f32_32x32x16_bf16 v[18:33], v[94:97], v[128:131], v[18:33]
	v_max_f32_e32 v83, v83, v83
	v_max_f32_e32 v82, v82, v82
	v_max_f32_e32 v82, v82, v83
	v_cmp_ge_f32_e32 vcc, s0, v82
	s_cmp_eq_u64 vcc, exec
	v_mov_b32_e32 v116, 1.0
	s_cbranch_scc0 .LBB0_344
